# stack: conflict-free K swizzle + 2-deep K-fragment prefetch in QK on top of one-barrier loop, counted PV waits and static prio
# speedup vs baseline: 1.0138x; 1.0138x over previous
; DI unsigned cvtpk(float lo, float hi) { unsigned r; asm volatile("v_cvt_pk_bf16_f32 %0, %1, %2" : "=v"(r) : "v"(lo), "v"(hi)); return r; }
; DI int v_st(int k, int c) { const int kk = (k & ~0xC) | ((k & 4) << 1) | ((k & 8) >> 1); return ((kk >> 3) * 4 + (c >> 5)) * 512 + ((kk & 7) * 32 + (c & 31)) * 2; }
; DI int v_rd_base(int lane) { return ((lane & 3) << 3) | (((lane >> 2) & 3) << 6) | (((lane >> 4) & 1) << 5) | (((lane >> 5) & 1) << 8); }
; #define SLOAD(i, k0) do { sr_[i].vs0 = ld8(&Vh[(long)((k0) + sr) * LDK + sc]); sr_[i].vs1 = ld8(&Vh[(long)((k0) + 32 + sr) * LDK + sc]); \
;     sr_[i].ks0 = ld8(&Kh[(long)((k0) + sr) * LDK + sc]); sr_[i].ks1 = ld8(&Kh[(long)((k0) + 32 + sr) * LDK + sc]); } while (0)
; #define SWRITE(b, i) do { *(bf16x8*)((char*)V_lds + (b) * SHM_V + vst0) = sr_[i].vs0;          \
;     *(bf16x8*)((char*)V_lds + (b) * SHM_V + vst1) = sr_[i].vs1; int kc = sc * 2;               \
;     *(bf16x8*)((char*)K_lds + (b) * SHM_K + KSWZ(sr, kc)) = sr_[i].ks0;                       \
;     *(bf16x8*)((char*)K_lds + (b) * SHM_K + KSWZ(32 + sr, kc)) = sr_[i].ks1; } while (0)
; DI int crow(int r, int hi) { return (r & 3) + 8 * (r >> 2) + 4 * hi; }
; DI void attn_dense_body(const bf16_t* __restrict__ Qb, const bf16_t* __restrict__ Kh, const bf16_t* __restrict__ Vh, ...
;     ...
;     for (int d0 = 0; d0 < 8; ++d0) { u32x4 w = {cvtpk(xf[d0][0], xf[d0][1]), cvtpk(xf[d0][2], xf[d0][3]), cvtpk(xf[d0][4], xf[d0][5]), cvtpk(xf[d0][6], xf[d0][7])}; qr[d0] = *reinterpret_cast<bf16x8*>(&w); }
;   }
;   const int sr = tid >> 4, sc = (tid & 15) * 8, vst0 = v_st(sr, sc), vst1 = v_st(32 + sr, sc);
;   const int vb0 = (int)(uintptr_t)V_lds + v_rd_base(lane);
;   struct { bf16x8 vs0, vs1, ks0, ks1; } sr_[2];
;     ...
;   f32x16 pA0, pA1, pB0, pB1; float mnA, mnB, alA, alB; bf16x8 pa0, pa1, pa2, pa3; const int NT = seq / KVBLK;
;   constexpr int SE = 0, SO = 1;
;   SLOAD(SE, 0); asm volatile("s_waitcnt vmcnt(0)" ::: "memory"); SWRITE(0, SE); __syncthreads();
;   qkt(pA0, pA1, K_lds, qr, r32, hi); partialSM(pA0, pA1, m_reg, mnA, alA);
.LBB0_834:
	s_or_b32 s4, s0, s12
	s_mov_b32 s5, s1
	s_lshl_b64 s[10:11], s[4:5], 1
	v_ashrrev_i32_e32 v176, 4, v160
	s_add_u32 s4, s96, s10
	v_cvt_pk_bf16_f32 v116, v114, v113
	v_cvt_pk_bf16_f32 v117, v106, v105
	v_cvt_pk_bf16_f32 v118, v98, v55
	v_cvt_pk_bf16_f32 v119, v90, v65
	v_cvt_pk_bf16_f32 v124, v88, v67
	v_cvt_pk_bf16_f32 v125, v86, v73
	v_cvt_pk_bf16_f32 v126, v84, v79
	v_cvt_pk_bf16_f32 v127, v82, v81
	v_cvt_pk_bf16_f32 v120, v40, v41
	v_cvt_pk_bf16_f32 v121, v42, v43
	v_cvt_pk_bf16_f32 v122, v44, v45
	v_cvt_pk_bf16_f32 v123, v46, v47
	v_cvt_pk_bf16_f32 v112, v56, v57
	v_cvt_pk_bf16_f32 v113, v58, v59
	v_cvt_pk_bf16_f32 v114, v60, v61
	v_cvt_pk_bf16_f32 v115, v62, v63
	v_cvt_pk_bf16_f32 v108, v76, v77
	v_cvt_pk_bf16_f32 v109, v74, v75
	v_cvt_pk_bf16_f32 v110, v70, v71
	v_cvt_pk_bf16_f32 v111, v68, v69
	v_cvt_pk_bf16_f32 v104, v38, v39
	v_cvt_pk_bf16_f32 v105, v36, v37
	v_cvt_pk_bf16_f32 v106, v34, v35
	v_cvt_pk_bf16_f32 v107, v32, v33
	v_cvt_pk_bf16_f32 v100, v28, v29
	v_cvt_pk_bf16_f32 v101, v30, v31
	v_cvt_pk_bf16_f32 v102, v18, v19
	v_cvt_pk_bf16_f32 v103, v20, v21
	v_cvt_pk_bf16_f32 v96, v22, v23
	v_cvt_pk_bf16_f32 v97, v26, v27
	v_cvt_pk_bf16_f32 v98, v16, v17
	v_lshlrev_b32_e32 v16, 3, v160
	v_add_u32_e32 v184, 32, v176
	s_addc_u32 s5, s97, s11
	v_readlane_b32 s13, v254, 38
	v_and_b32_e32 v178, 0x78, v16
	v_ashrrev_i32_e32 v177, 31, v176
	v_ashrrev_i32_e32 v185, 31, v184
	s_add_u32 s10, s13, s10
	v_readlane_b32 s13, v254, 39
	v_lshlrev_b32_e32 v72, 1, v178
	v_lshlrev_b64 v[48:49], 9, v[176:177]
	v_lshlrev_b64 v[12:13], 9, v[184:185]
	s_addc_u32 s11, s13, s11
	v_or_b32_e32 v8, v48, v72
	v_mov_b32_e32 v9, v49
	v_or_b32_e32 v12, v12, v72
	v_lshl_add_u64 v[0:1], s[10:11], 0, v[8:9]
	v_lshl_add_u64 v[4:5], s[10:11], 0, v[12:13]
	v_cvt_pk_bf16_f32 v99, v24, v25
	global_load_dwordx4 v[0:3], v[0:1], off
	s_nop 0
	global_load_dwordx4 v[4:7], v[4:5], off
	v_lshl_add_u64 v[8:9], s[4:5], 0, v[8:9]
	global_load_dwordx4 v[8:11], v[8:9], off
	v_lshl_add_u64 v[12:13], s[4:5], 0, v[12:13]
	global_load_dwordx4 v[12:15], v[12:13], off
	v_and_b32_e32 v18, 0xfffff0, v176
	v_lshlrev_b32_e32 v19, 1, v176
	v_lshrrev_b32_e32 v20, 1, v176
	v_and_b32_e32 v21, 3, v176
	v_and_or_b32 v18, v19, 8, v18
	v_and_or_b32 v19, v20, 4, v21
	v_and_b32_e32 v20, 0xfffff0, v184
	v_lshlrev_b32_e32 v21, 1, v184
	v_bfe_u32 v16, v16, 5, 2
	v_lshrrev_b32_e32 v18, 1, v18
	v_and_or_b32 v20, v21, 8, v20
	v_or_b32_e32 v18, v18, v16
	v_lshrrev_b32_e32 v20, 1, v20
	v_lshlrev_b32_e32 v19, 6, v19
	v_and_b32_e32 v23, 48, v72
	v_lshlrev_b32_e32 v18, 9, v18
	v_or_b32_e32 v16, v20, v16
	v_and_b32_e32 v17, 0x70, v160
	v_lshrrev_b32_e32 v24, 1, v160
	v_and_b32_e32 v24, 0x80, v24
	v_or_b32_e32 v17, v17, v24
	v_lshlrev_b32_e32 v22, 8, v176
	v_or3_b32 v18, v18, v19, v23
	v_lshlrev_b32_e32 v16, 9, v16
	v_bitop3_b32 v21, v72, v22, v17 bitop3:0xde
	v_or3_b32 v16, v16, v19, v23
	v_add_u32_e32 v204, 0, v18
	v_add_u32_e32 v203, 0, v21
	s_waitcnt vmcnt(0)
	v_add_u32_e32 v205, 0, v16
	s_waitcnt vmcnt(3)
	ds_write_b128 v204, v[0:3]
	s_waitcnt vmcnt(2)
	ds_write_b128 v205, v[4:7]
	s_waitcnt vmcnt(1)
	ds_write_b128 v203, v[8:11] offset:32768
	v_lshlrev_b32_e32 v0, 8, v184
	v_bitop3_b32 v0, v72, v0, v17 bitop3:0xde
	v_add_u32_e32 v206, 0, v0
	v_lshlrev_b32_e32 v0, 4, v196
	v_lshlrev_b32_e32 v66, 8, v196
	v_and_b32_e32 v67, 0x70, v0
	v_lshrrev_b32_e32 v24, 1, v0
	v_and_b32_e32 v24, 0x80, v24
	v_or_b32_e32 v67, v67, v24
	v_bitop3_b32 v0, v180, v66, v67 bitop3:0xde
	v_add_u32_e32 v207, 0, v0
	s_waitcnt vmcnt(0)
	ds_write_b128 v206, v[12:15] offset:32768
	s_waitcnt lgkmcnt(0)
	s_barrier
	ds_read_b128 v[0:3], v207 offset:32768
	ds_read_b128 v[4:7], v207 offset:40960
	s_waitcnt lgkmcnt(1)
	v_mfma_f32_32x32x16_bf16 v[16:31], v[0:3], v[116:119], 0
	v_or_b32_e32 v0, 32, v180
	v_bitop3_b32 v0, v0, v66, v67 bitop3:0xde
	v_add_u32_e32 v210, 0, v0
	s_add_i32 s13, 0, 0x10000
	v_and_b32_e32 v74, 63, v160
	v_lshlrev_b32_e32 v68, 3, v74
	v_add_u32_e32 v186, 64, v176
	s_waitcnt lgkmcnt(0)
	v_mfma_f32_32x32x16_bf16 v[32:47], v[4:7], v[116:119], 0
	ds_read_b128 v[0:3], v210 offset:32768
	ds_read_b128 v[4:7], v210 offset:40960
	v_ashrrev_i32_e32 v187, 31, v186
	v_add_u32_e32 v188, 0x60, v176
	v_lshlrev_b64 v[8:9], 9, v[186:187]
	v_ashrrev_i32_e32 v189, 31, v188
	v_lshlrev_b32_e32 v70, 1, v74
	v_or_b32_e32 v8, v8, v72
	s_waitcnt lgkmcnt(1)
	v_mfma_f32_32x32x16_bf16 v[16:31], v[0:3], v[124:127], v[16:31]
	v_or_b32_e32 v0, 64, v180
	v_bitop3_b32 v0, v0, v66, v67 bitop3:0xde
	v_add_u32_e32 v211, 0, v0
	v_lshlrev_b64 v[12:13], 9, v[188:189]
	v_lshl_add_u64 v[10:11], s[10:11], 0, v[8:9]
	v_or_b32_e32 v12, v12, v72
	v_lshl_add_u64 v[8:9], s[4:5], 0, v[8:9]
	s_waitcnt lgkmcnt(0)
	v_mfma_f32_32x32x16_bf16 v[32:47], v[4:7], v[124:127], v[32:47]
	ds_read_b128 v[0:3], v211 offset:32768
	ds_read_b128 v[4:7], v211 offset:40960
	v_lshl_add_u64 v[14:15], s[10:11], 0, v[12:13]
	v_add_u32_e32 v190, 0x80, v176
	v_ashrrev_i32_e32 v191, 31, v190
	v_add_u32_e32 v192, 0xa0, v176
	v_ashrrev_i32_e32 v193, 31, v192
	s_cmp_lg_u32 0, -1
	s_waitcnt lgkmcnt(1)
	v_mfma_f32_32x32x16_bf16 v[16:31], v[0:3], v[120:123], v[16:31]
	v_or_b32_e32 v0, 0x60, v180
	v_bitop3_b32 v0, v0, v66, v67 bitop3:0xde
	v_add_u32_e32 v208, 0, v0
	s_mov_b32 s69, s68
	s_mov_b32 s70, s68
	s_mov_b32 s71, s68
	s_mov_b32 s72, s68
	s_waitcnt lgkmcnt(0)
	v_mfma_f32_32x32x16_bf16 v[32:47], v[4:7], v[120:123], v[32:47]
	ds_read_b128 v[0:3], v208 offset:32768
	ds_read_b128 v[4:7], v208 offset:40960
	s_mov_b32 s73, s68
	s_mov_b32 s74, s68
	s_mov_b32 s75, s68
	s_mov_b32 s76, s68
	s_mov_b32 s77, s68
	s_mov_b32 s78, s68
	s_waitcnt lgkmcnt(1)
; #define SLOAD(i, k0) do { sr_[i].vs0 = ld8(&Vh[(long)((k0) + sr) * LDK + sc]); sr_[i].vs1 = ld8(&Vh[(long)((k0) + 32 + sr) * LDK + sc]); \
;     sr_[i].ks0 = ld8(&Kh[(long)((k0) + sr) * LDK + sc]); sr_[i].ks1 = ld8(&Kh[(long)((k0) + 32 + sr) * LDK + sc]); } while (0)
; #define SWRITE(b, i) do { *(bf16x8*)((char*)V_lds + (b) * SHM_V + vst0) = sr_[i].vs0;          \
;     *(bf16x8*)((char*)V_lds + (b) * SHM_V + vst1) = sr_[i].vs1; int kc = sc * 2;               \
;     *(bf16x8*)((char*)K_lds + (b) * SHM_K + KSWZ(sr, kc)) = sr_[i].ks0;                       \
;     *(bf16x8*)((char*)K_lds + (b) * SHM_K + KSWZ(32 + sr, kc)) = sr_[i].ks1; } while (0)
; DI void qkt(f32x16& p0, f32x16& p1, const bf16_t* Ks, const bf16x8* qr, int r32, int hi) {
;   p0 = f32x16{}; p1 = f32x16{};
;   for (int d0 = 0; d0 < 8; ++d0) { int cb = (d0 * 16 + hi * 8) * 2;
;     bf16x8 b0 = *reinterpret_cast<const bf16x8*>((const char*)Ks + KSWZ(r32, cb));
;     bf16x8 b1 = *reinterpret_cast<const bf16x8*>((const char*)Ks + KSWZ(32 + r32, cb));
;     p0 = __builtin_amdgcn_mfma_f32_32x32x16_bf16(b0, qr[d0], p0, 0, 0, 0);
;     p1 = __builtin_amdgcn_mfma_f32_32x32x16_bf16(b1, qr[d0], p1, 0, 0, 0); }
; }
; DI void attn_dense_body(const bf16_t* __restrict__ Qb, const bf16_t* __restrict__ Kh, const bf16_t* __restrict__ Vh, ...
;     ...
;   SLOAD(SE, 0); asm volatile("s_waitcnt vmcnt(0)" ::: "memory"); SWRITE(0, SE); __syncthreads();
;   qkt(pA0, pA1, K_lds, qr, r32, hi); partialSM(pA0, pA1, m_reg, mnA, alA);
;   SLOAD(SO, KVBLK); if (2 < NT) SLOAD(SE, 2 * KVBLK);
	v_mfma_f32_32x32x16_bf16 v[16:31], v[0:3], v[112:115], v[16:31]
	v_or_b32_e32 v0, 0x80, v180
	v_bitop3_b32 v0, v0, v66, v67 bitop3:0xde
	v_add_u32_e32 v209, 0, v0
	ds_read_b128 v[0:3], v209 offset:32768
	s_mov_b32 s79, s68
	s_mov_b32 s80, s68
	s_mov_b32 s81, s68
	s_waitcnt lgkmcnt(1)
	v_mfma_f32_32x32x16_bf16 v[32:47], v[4:7], v[112:115], v[32:47]
	ds_read_b128 v[4:7], v209 offset:40960
	s_mov_b32 s82, s68
	s_mov_b32 s83, s68
	s_mov_b32 s16, 4
	v_mov_b32_e32 v200, 0
	s_waitcnt lgkmcnt(1)
	v_mfma_f32_32x32x16_bf16 v[16:31], v[0:3], v[108:111], v[16:31]
	v_and_b32_e32 v0, 0x3fffffc0, v160
	v_lshl_add_u32 v198, v0, 2, s13
	v_or_b32_e32 v0, 0xa0, v180
	v_bitop3_b32 v0, v0, v66, v67 bitop3:0xde
	v_add_u32_e32 v212, 0, v0
	ds_read_b128 v[0:3], v212 offset:32768
	s_cselect_b32 s13, 0, 0
	s_waitcnt lgkmcnt(1)
	v_mfma_f32_32x32x16_bf16 v[32:47], v[4:7], v[108:111], v[32:47]
	v_lshlrev_b32_e32 v4, 4, v74
	v_and_b32_e32 v4, 0xc0, v4
	v_and_or_b32 v69, v68, 24, v4
	ds_read_b128 v[4:7], v212 offset:40960
	v_lshl_add_u32 v199, v196, 2, v198
	s_waitcnt lgkmcnt(1)
	v_mfma_f32_32x32x16_bf16 v[16:31], v[0:3], v[104:107], v[16:31]
	v_or_b32_e32 v0, 0xc0, v180
	v_bitop3_b32 v0, v0, v66, v67 bitop3:0xde
	v_add_u32_e32 v213, 0, v0
	ds_read_b128 v[0:3], v213 offset:32768
	global_load_dwordx4 v[50:53], v[10:11], off
	global_load_dwordx4 v[54:57], v[14:15], off
	v_lshl_add_u64 v[10:11], s[4:5], 0, v[12:13]
	global_load_dwordx4 v[58:61], v[8:9], off
	global_load_dwordx4 v[62:65], v[10:11], off
	s_waitcnt lgkmcnt(0)
	v_mfma_f32_32x32x16_bf16 v[16:31], v[0:3], v[100:103], v[16:31]
	v_or_b32_e32 v0, 0xe0, v180
	v_bitop3_b32 v0, v0, v66, v67 bitop3:0xde
	v_add_u32_e32 v214, 0, v0
	ds_read_b128 v[0:3], v214 offset:32768
	v_mfma_f32_32x32x16_bf16 v[32:47], v[4:7], v[104:107], v[32:47]
	v_and_b32_e32 v4, 32, v70
	v_and_b32_e32 v5, 0x100, v68
	v_or3_b32 v75, v69, v4, v5
	ds_read_b128 v[4:7], v213 offset:40960
	ds_read_b128 v[66:69], v214 offset:40960
	v_lshlrev_b64 v[70:71], 9, v[192:193]
	v_or_b32_e32 v70, v70, v72
	s_waitcnt lgkmcnt(1)
	v_mfma_f32_32x32x16_bf16 v[32:47], v[4:7], v[100:103], v[32:47]
	v_add_u32_e32 v202, s13, v75
	v_mfma_f32_32x32x16_bf16 v[16:31], v[0:3], v[96:99], v[16:31]
	v_mov_b64_e32 v[0:1], s[68:69]
	v_mov_b64_e32 v[14:15], s[82:83]
	v_mov_b64_e32 v[2:3], s[70:71]
	v_mov_b64_e32 v[4:5], s[72:73]
	v_mov_b64_e32 v[6:7], s[74:75]
	v_mov_b64_e32 v[8:9], s[76:77]
	v_mov_b64_e32 v[10:11], s[78:79]
	s_waitcnt lgkmcnt(0)
	v_mfma_f32_32x32x16_bf16 v[32:47], v[66:69], v[96:99], v[32:47]
	s_nop 2
	v_max_f32_e32 v66, v17, v17
	v_max_f32_e32 v67, v16, v16
	v_max_f32_e32 v66, v67, v66
	v_max3_f32 v66, v66, v18, v19
	v_max3_f32 v66, v66, v20, v21
	v_max3_f32 v66, v66, v22, v23
	v_max3_f32 v66, v66, v24, v25
	v_max3_f32 v66, v66, v26, v27
	v_max3_f32 v66, v66, v28, v29
	v_max3_f32 v66, v66, v30, v31
	v_max3_f32 v66, v66, v32, v33
	v_max3_f32 v66, v66, v34, v35
	v_max3_f32 v66, v66, v36, v37
	v_max3_f32 v66, v66, v38, v39
	v_max3_f32 v66, v66, v40, v41
	v_max3_f32 v66, v66, v42, v43
	v_max3_f32 v66, v66, v44, v45
	v_max3_f32 v76, v66, v46, v47
	v_lshlrev_b64 v[66:67], 9, v[190:191]
	v_or_b32_e32 v66, v66, v72
	v_lshl_add_u64 v[68:69], s[10:11], 0, v[66:67]
	v_lshl_add_u64 v[66:67], s[4:5], 0, v[66:67]
	v_lshl_add_u64 v[72:73], s[10:11], 0, v[70:71]
	global_load_dwordx4 v[128:131], v[68:69], off
	global_load_dwordx4 v[136:139], v[72:73], off
	v_lshl_add_u64 v[68:69], s[4:5], 0, v[70:71]
	global_load_dwordx4 v[132:135], v[66:67], off
	global_load_dwordx4 v[140:143], v[68:69], off
	v_mov_b32_e32 v77, v76
	s_nop 1
	v_permlane32_swap_b32_e32 v76, v77
	v_max_f32_e32 v66, v77, v77
	v_max_f32_e32 v67, v76, v76
	v_max_f32_e32 v66, v67, v66
	s_waitcnt vmcnt(4)
; #define SLOAD(i, k0) do { sr_[i].vs0 = ld8(&Vh[(long)((k0) + sr) * LDK + sc]); sr_[i].vs1 = ld8(&Vh[(long)((k0) + 32 + sr) * LDK + sc]); \
;     sr_[i].ks0 = ld8(&Kh[(long)((k0) + sr) * LDK + sc]); sr_[i].ks1 = ld8(&Kh[(long)((k0) + 32 + sr) * LDK + sc]); } while (0)
; #define SWRITE(b, i) do { *(bf16x8*)((char*)V_lds + (b) * SHM_V + vst0) = sr_[i].vs0;          \
;     *(bf16x8*)((char*)V_lds + (b) * SHM_V + vst1) = sr_[i].vs1; int kc = sc * 2;               \
;     *(bf16x8*)((char*)K_lds + (b) * SHM_K + KSWZ(sr, kc)) = sr_[i].ks0;                       \
;     *(bf16x8*)((char*)K_lds + (b) * SHM_K + KSWZ(32 + sr, kc)) = sr_[i].ks1; } while (0)
; #define SWAIT() asm volatile("s_waitcnt vmcnt(4)" ::: "memory")
; DI void partialSM(f32x16& p0, f32x16& p1, float& m_reg, float& mn, float& alpha) {
;   constexpr float C = SCALE * 1.4426950408889634f;
;   float pmax = p0[0]; for (int r = 1; r < 16; ++r) pmax = fmaxf(pmax, p0[r]); for (int r = 0; r < 16; ++r) pmax = fmaxf(pmax, p1[r]);
;   { auto rr = __builtin_amdgcn_permlane32_swap(__float_as_uint(pmax), __float_as_uint(pmax), false, false);
;     pmax = fmaxf(__uint_as_float(rr[0]), __uint_as_float(rr[1])); }
;   if (__builtin_expect(__all(pmax - m_reg <= THR / SCALE), 1)) { mn = m_reg; alpha = 1.f; }
;   else { mn = fmaxf(m_reg, pmax); alpha = __builtin_amdgcn_exp2f((m_reg - mn) * C); m_reg = mn; }
;   float mnC = -mn * C;
;   for (int r = 0; r < 16; ++r) p0[r] = fmaf(p0[r], C, mnC); for (int r = 0; r < 16; ++r) p1[r] = fmaf(p1[r], C, mnC);
;   for (int r = 0; r < 16; ++r) p0[r] = __builtin_amdgcn_exp2f(p0[r]);
; }
; DI void attn_dense_body(const bf16_t* __restrict__ Qb, const bf16_t* __restrict__ Kh, const bf16_t* __restrict__ Vh, ...
;     ...
;   f32x16 pA0, pA1, pB0, pB1; float mnA, mnB, alA, alB; bf16x8 pa0, pa1, pa2, pa3; const int NT = seq / KVBLK;
;   constexpr int SE = 0, SO = 1;
;   SLOAD(SE, 0); asm volatile("s_waitcnt vmcnt(0)" ::: "memory"); SWRITE(0, SE); __syncthreads();
;   qkt(pA0, pA1, K_lds, qr, r32, hi); partialSM(pA0, pA1, m_reg, mnA, alA);
;   SLOAD(SO, KVBLK); if (2 < NT) SLOAD(SE, 2 * KVBLK);
;   SWAIT(); SWRITE(1, SO); __syncthreads();
	s_waitcnt vmcnt(7)
	ds_write_b128 v204, v[50:53] offset:16384
	s_waitcnt vmcnt(6)
	ds_write_b128 v205, v[54:57] offset:16384
	s_waitcnt vmcnt(5)
	ds_write_b128 v203, v[58:61] offset:49152
	s_waitcnt vmcnt(4)
	ds_write_b128 v206, v[62:65] offset:49152
	v_max_f32_e32 v50, 0xf149f2ca, v66
	v_sub_f32_e32 v51, 0xf149f2ca, v50
	v_mul_f32_e32 v51, 0x3e0293ee, v51
	v_add_f32_e32 v67, 0x7149f2ca, v66
	v_exp_f32_e32 v51, v51
	v_cmp_ge_f32_e32 vcc, s95, v67
	s_cmp_eq_u64 vcc, exec
	s_cselect_b64 vcc, -1, 0
	v_cndmask_b32_e64 v215, v51, 1.0, vcc
	v_mov_b32_e32 v51, 0xf149f2ca
	v_cndmask_b32_e32 v168, v50, v51, vcc
	v_mul_f32_e32 v50, 0xbe0293ee, v168
	v_fmamk_f32 v16, v16, 0x3e0293ee, v50
	v_exp_f32_e32 v161, v16
	v_fmamk_f32 v16, v17, 0x3e0293ee, v50
	v_exp_f32_e32 v175, v16
	v_fmamk_f32 v16, v18, 0x3e0293ee, v50
	v_exp_f32_e32 v162, v16
	v_fmamk_f32 v16, v19, 0x3e0293ee, v50
	v_exp_f32_e32 v219, v16
	v_fmamk_f32 v16, v20, 0x3e0293ee, v50
	v_exp_f32_e32 v174, v16
	v_fmamk_f32 v16, v21, 0x3e0293ee, v50
	v_exp_f32_e32 v222, v16
	v_fmamk_f32 v16, v22, 0x3e0293ee, v50
	v_exp_f32_e32 v163, v16
	v_fmamk_f32 v16, v23, 0x3e0293ee, v50
	v_exp_f32_e32 v173, v16
	v_fmamk_f32 v16, v24, 0x3e0293ee, v50
	v_exp_f32_e32 v164, v16
	v_fmamk_f32 v16, v25, 0x3e0293ee, v50
	v_exp_f32_e32 v171, v16
	v_fmamk_f32 v16, v26, 0x3e0293ee, v50
	v_exp_f32_e32 v165, v16
	v_fmamk_f32 v16, v27, 0x3e0293ee, v50
	s_addk_i32 s13, 0x4000
	v_exp_f32_e32 v172, v16
	v_fmamk_f32 v16, v28, 0x3e0293ee, v50
	s_add_u32 s0, s0, s12
	v_exp_f32_e32 v166, v16
	v_fmamk_f32 v16, v29, 0x3e0293ee, v50
	s_addc_u32 s1, s1, 0
	v_pk_fma_f32 v[144:145], v[46:47], s[42:43], v[50:51] op_sel_hi:[1,0,0]
	v_pk_fma_f32 v[150:151], v[44:45], s[42:43], v[50:51] op_sel_hi:[1,0,0]
	v_pk_fma_f32 v[154:155], v[42:43], s[42:43], v[50:51] op_sel_hi:[1,0,0]
	v_pk_fma_f32 v[146:147], v[40:41], s[42:43], v[50:51] op_sel_hi:[1,0,0]
	v_pk_fma_f32 v[148:149], v[38:39], s[42:43], v[50:51] op_sel_hi:[1,0,0]
	v_pk_fma_f32 v[152:153], v[36:37], s[42:43], v[50:51] op_sel_hi:[1,0,0]
	v_pk_fma_f32 v[156:157], v[34:35], s[42:43], v[50:51] op_sel_hi:[1,0,0]
	v_pk_fma_f32 v[158:159], v[32:33], s[42:43], v[50:51] op_sel_hi:[1,0,0]
	v_exp_f32_e32 v169, v16
	v_fmamk_f32 v16, v30, 0x3e0293ee, v50
	v_fmac_f32_e32 v50, 0x3e0293ee, v31
	s_lshl_b64 s[0:1], s[0:1], 1
	v_readlane_b32 s10, v255, 31
	v_exp_f32_e32 v167, v16
	v_exp_f32_e32 v170, v50
	v_and_b32_e32 v16, 15, v160
	s_add_u32 s0, s10, s0
	v_readlane_b32 s10, v255, 32
	v_lshl_or_b32 v48, v16, 4, v48
	s_addc_u32 s1, s10, s1
	v_mov_b64_e32 v[12:13], s[80:81]
	v_lshl_add_u64 v[194:195], s[0:1], 0, v[48:49]
	v_mov_b64_e32 v[62:63], v[14:15]
	v_mov_b64_e32 v[46:47], v[14:15]
	v_mov_b64_e32 v[30:31], v[14:15]
	v_cmp_gt_u32_e64 s[4:5], 32, v74
	v_add_u32_e32 v201, s13, v75
	v_mov_b64_e32 v[60:61], v[12:13]
	v_mov_b64_e32 v[58:59], v[10:11]
	v_mov_b64_e32 v[56:57], v[8:9]
	v_mov_b64_e32 v[54:55], v[6:7]
	v_mov_b64_e32 v[52:53], v[4:5]
	v_mov_b64_e32 v[50:51], v[2:3]
	v_mov_b64_e32 v[48:49], v[0:1]
	v_mov_b64_e32 v[44:45], v[12:13]
	v_mov_b64_e32 v[42:43], v[10:11]
	v_mov_b64_e32 v[40:41], v[8:9]
	v_mov_b64_e32 v[38:39], v[6:7]
	v_mov_b64_e32 v[36:37], v[4:5]
	v_mov_b64_e32 v[34:35], v[2:3]
	v_mov_b64_e32 v[32:33], v[0:1]
	v_mov_b64_e32 v[28:29], v[12:13]
	v_mov_b64_e32 v[26:27], v[10:11]
	v_mov_b64_e32 v[24:25], v[8:9]
	v_mov_b64_e32 v[22:23], v[6:7]
	v_mov_b64_e32 v[20:21], v[4:5]
	v_mov_b64_e32 v[18:19], v[2:3]
	v_mov_b64_e32 v[16:17], v[0:1]
	v_readfirstlane_b32 s100, v252
	s_nop 3
	s_lshr_b32 s100, s100, 6
	s_cmp_ge_u32 s100, 4
	s_cbranch_scc0 .Lattn_prio_done
	s_setprio 1

; DI void finishSM(f32x16& p0, f32x16& p1, float alpha, float& l_reg, bf16x8& pa0, bf16x8& pa1, bf16x8& pa2, bf16x8& pa3) {
;   for (int r = 0; r < 16; ++r) p1[r] = __builtin_amdgcn_exp2f(p1[r]);
;   float ps = 0; for (int r = 0; r < 16; ++r) ps += p0[r]; for (int r = 0; r < 16; ++r) ps += p1[r];
;   { auto rr = __builtin_amdgcn_permlane32_swap(__float_as_uint(ps), __float_as_uint(ps), false, false);
;     ps = __uint_as_float(rr[0]) + __uint_as_float(rr[1]); }
;   l_reg = l_reg * alpha + ps;
; DI void qkt(f32x16& p0, f32x16& p1, const bf16_t* Ks, const bf16x8* qr, int r32, int hi) {
;   p0 = f32x16{}; p1 = f32x16{};
;   for (int d0 = 0; d0 < 8; ++d0) { int cb = (d0 * 16 + hi * 8) * 2;
;     bf16x8 b0 = *reinterpret_cast<const bf16x8*>((const char*)Ks + KSWZ(r32, cb));
;     bf16x8 b1 = *reinterpret_cast<const bf16x8*>((const char*)Ks + KSWZ(32 + r32, cb));
;     p0 = __builtin_amdgcn_mfma_f32_32x32x16_bf16(b0, qr[d0], p0, 0, 0, 0);
;     p1 = __builtin_amdgcn_mfma_f32_32x32x16_bf16(b1, qr[d0], p1, 0, 0, 0); }
; }
.LBB0_835:
	ds_read_b128 v[64:67], v207 offset:49152
	ds_read_b128 v[68:71], v207 offset:57344
	ds_read_b128 v[232:235], v210 offset:49152
	ds_read_b128 v[236:239], v210 offset:57344
	v_add_f32_e32 v160, 0, v161
	v_add_f32_e32 v160, v175, v160
	s_waitcnt lgkmcnt(3)
	v_mfma_f32_32x32x16_bf16 v[80:95], v[64:67], v[116:119], 0
	v_add_f32_e32 v160, v162, v160
	v_add_f32_e32 v160, v219, v160
	v_add_f32_e32 v160, v174, v160
	v_add_f32_e32 v160, v222, v160
	v_add_f32_e32 v160, v163, v160
	v_add_f32_e32 v160, v173, v160
	v_add_f32_e32 v160, v164, v160
	s_waitcnt lgkmcnt(2)
	v_mfma_f32_32x32x16_bf16 v[64:79], v[68:71], v[116:119], 0
	ds_read_b128 v[240:243], v211 offset:49152
	ds_read_b128 v[244:247], v211 offset:57344
	v_add_f32_e32 v160, v171, v160
	v_add_f32_e32 v160, v165, v160
	v_add_f32_e32 v160, v172, v160
	v_exp_f32_e32 v158, v158
	v_add_f32_e32 v160, v166, v160
	v_exp_f32_e32 v159, v159
	v_add_f32_e32 v160, v169, v160
	s_waitcnt lgkmcnt(3)
	v_mfma_f32_32x32x16_bf16 v[80:95], v[232:235], v[124:127], v[80:95]
	v_exp_f32_e32 v156, v156
	v_add_f32_e32 v160, v167, v160
	v_exp_f32_e32 v157, v157
	v_add_f32_e32 v160, v170, v160
	v_exp_f32_e32 v152, v152
	v_add_f32_e32 v160, v158, v160
	v_exp_f32_e32 v153, v153
	s_waitcnt lgkmcnt(2)
	v_mfma_f32_32x32x16_bf16 v[64:79], v[236:239], v[124:127], v[64:79]
	ds_read_b128 v[232:235], v208 offset:49152
	ds_read_b128 v[236:239], v208 offset:57344
	v_add_f32_e32 v160, v159, v160
	v_exp_f32_e32 v148, v148
	v_add_f32_e32 v160, v156, v160
	v_exp_f32_e32 v149, v149
	v_add_f32_e32 v160, v157, v160
	v_exp_f32_e32 v146, v146
	s_waitcnt lgkmcnt(3)
	v_mfma_f32_32x32x16_bf16 v[80:95], v[240:243], v[120:123], v[80:95]
	v_add_f32_e32 v160, v152, v160
	v_exp_f32_e32 v147, v147
	v_add_f32_e32 v160, v153, v160
	v_exp_f32_e32 v154, v154
	v_add_f32_e32 v160, v148, v160
	v_exp_f32_e32 v155, v155
	v_add_f32_e32 v160, v149, v160
	s_waitcnt lgkmcnt(2)
	v_mfma_f32_32x32x16_bf16 v[64:79], v[244:247], v[120:123], v[64:79]
	ds_read_b128 v[240:243], v209 offset:49152
	ds_read_b128 v[244:247], v209 offset:57344
	v_exp_f32_e32 v150, v150
	v_add_f32_e32 v160, v146, v160
	v_exp_f32_e32 v151, v151
	v_add_f32_e32 v160, v147, v160
	v_exp_f32_e32 v144, v144
	v_add_f32_e32 v160, v154, v160
	s_waitcnt lgkmcnt(3)
	v_mfma_f32_32x32x16_bf16 v[80:95], v[232:235], v[112:115], v[80:95]
	v_exp_f32_e32 v145, v145
	v_add_f32_e32 v160, v155, v160
	v_add_f32_e32 v160, v150, v160
	v_add_f32_e32 v160, v151, v160
	v_add_f32_e32 v160, v144, v160
	v_add_f32_e32 v216, v145, v160
	v_mov_b32_e32 v217, v216
	s_waitcnt lgkmcnt(2)
	v_mfma_f32_32x32x16_bf16 v[64:79], v[236:239], v[112:115], v[64:79]
	ds_read_b128 v[232:235], v212 offset:49152
	ds_read_b128 v[236:239], v212 offset:57344
	v_permlane32_swap_b32_e32 v216, v217
	s_waitcnt lgkmcnt(3)
	v_mfma_f32_32x32x16_bf16 v[80:95], v[240:243], v[108:111], v[80:95]
	s_waitcnt lgkmcnt(2)
	v_mfma_f32_32x32x16_bf16 v[64:79], v[244:247], v[108:111], v[64:79]
	ds_read_b128 v[240:243], v213 offset:49152
	ds_read_b128 v[244:247], v213 offset:57344
	s_waitcnt lgkmcnt(3)
	v_mfma_f32_32x32x16_bf16 v[80:95], v[232:235], v[104:107], v[80:95]
	s_waitcnt lgkmcnt(2)
	v_mfma_f32_32x32x16_bf16 v[64:79], v[236:239], v[104:107], v[64:79]
	ds_read_b128 v[232:235], v214 offset:49152
	ds_read_b128 v[236:239], v214 offset:57344
	s_waitcnt lgkmcnt(3)
	v_mfma_f32_32x32x16_bf16 v[80:95], v[240:243], v[100:103], v[80:95]
	s_waitcnt lgkmcnt(2)
	v_mfma_f32_32x32x16_bf16 v[64:79], v[244:247], v[100:103], v[64:79]
	v_cvt_pk_bf16_f32 v160, v161, v175
	v_cvt_pk_bf16_f32 v161, v162, v219
	v_cvt_pk_bf16_f32 v162, v174, v222
	v_cvt_pk_bf16_f32 v163, v163, v173
	v_cvt_pk_bf16_f32 v164, v164, v171
	v_cvt_pk_bf16_f32 v165, v165, v172
	s_waitcnt lgkmcnt(1)
	v_mfma_f32_32x32x16_bf16 v[80:95], v[232:235], v[96:99], v[80:95]
	v_cvt_pk_bf16_f32 v166, v166, v169
	v_cvt_pk_bf16_f32 v167, v167, v170
	v_cvt_pk_bf16_f32 v170, v158, v159
	v_cvt_pk_bf16_f32 v171, v156, v157
	v_cvt_pk_bf16_f32 v172, v152, v153
	v_cvt_pk_bf16_f32 v173, v148, v149
	v_cvt_pk_bf16_f32 v218, v146, v147
	s_waitcnt lgkmcnt(0)
	v_mfma_f32_32x32x16_bf16 v[64:79], v[236:239], v[96:99], v[64:79]
	v_cvt_pk_bf16_f32 v219, v154, v155
	v_cvt_pk_bf16_f32 v220, v150, v151
	v_permlane32_swap_b32_e32 v160, v162
	v_cvt_pk_bf16_f32 v221, v144, v145
	v_permlane32_swap_b32_e32 v218, v220
	v_permlane32_swap_b32_e32 v161, v163
	v_permlane32_swap_b32_e32 v164, v166
	v_permlane32_swap_b32_e32 v165, v167
	v_permlane32_swap_b32_e32 v170, v172
	v_permlane32_swap_b32_e32 v171, v173
	v_permlane32_swap_b32_e32 v219, v221
	s_waitcnt vmcnt(0)
	ds_write_b128 v203, v[132:135] offset:32768
	ds_write_b128 v206, v[140:143] offset:32768
	s_mov_b32 s0, 0xffff4000
	v_add_co_u32_e32 v144, vcc, s0, v194
	s_movk_i32 s0, 0x8000
	s_nop 0
	v_addc_co_u32_e32 v145, vcc, -1, v195, vcc
	v_add_co_u32_e32 v148, vcc, s0, v194
	s_mov_b32 s0, 0xfeef4000
	s_nop 0
	v_addc_co_u32_e32 v149, vcc, -1, v195, vcc
	v_add_co_u32_e32 v152, vcc, s0, v194
	s_mov_b32 s0, 0xfeef8000
	s_nop 0
	v_addc_co_u32_e32 v153, vcc, -1, v195, vcc
	v_add_co_u32_e32 v156, vcc, s0, v194
	global_load_dwordx4 v[144:147], v[144:145], off
	s_nop 0
	global_load_dwordx4 v[148:151], v[148:149], off
	v_addc_co_u32_e32 v157, vcc, -1, v195, vcc
	global_load_dwordx4 v[152:155], v[152:153], off
	s_nop 0
	global_load_dwordx4 v[156:159], v[156:157], off
	ds_read_b64_tr_b16 v[232:233], v202 offset:0
	ds_read_b64_tr_b16 v[234:235], v202 offset:0x800
	ds_read_b64_tr_b16 v[236:237], v202 offset:0x1000
	ds_read_b64_tr_b16 v[238:239], v202 offset:0x1800
	ds_read_b64_tr_b16 v[240:241], v202 offset:0x2000
	ds_read_b64_tr_b16 v[242:243], v202 offset:0x2800
	ds_read_b64_tr_b16 v[244:245], v202 offset:0x3000
	ds_read_b64_tr_b16 v[246:247], v202 offset:0x3800
	s_waitcnt lgkmcnt(6)
; #define SBAR() __builtin_amdgcn_sched_barrier(0)
; DI void partialSM(f32x16& p0, f32x16& p1, float& m_reg, float& mn, float& alpha) {
;   constexpr float C = SCALE * 1.4426950408889634f;
;   float pmax = p0[0]; for (int r = 1; r < 16; ++r) pmax = fmaxf(pmax, p0[r]); for (int r = 0; r < 16; ++r) pmax = fmaxf(pmax, p1[r]);
;   { auto rr = __builtin_amdgcn_permlane32_swap(__float_as_uint(pmax), __float_as_uint(pmax), false, false);
;     pmax = fmaxf(__uint_as_float(rr[0]), __uint_as_float(rr[1])); }
;   if (__builtin_expect(__all(pmax - m_reg <= THR / SCALE), 1)) { mn = m_reg; alpha = 1.f; }
;   else { mn = fmaxf(m_reg, pmax); alpha = __builtin_amdgcn_exp2f((m_reg - mn) * C); m_reg = mn; }
;   float mnC = -mn * C;
;   for (int r = 0; r < 16; ++r) p0[r] = fmaf(p0[r], C, mnC); for (int r = 0; r < 16; ++r) p1[r] = fmaf(p1[r], C, mnC);
;   for (int r = 0; r < 16; ++r) p0[r] = __builtin_amdgcn_exp2f(p0[r]);
; }
; template <int D0> DI void pv_one(f32x16& od, int vb, bf16x8 pa0, bf16x8 pa1, bf16x8 pa2, bf16x8 pa3) {
;   const s16x4 l0 = tr_read<v_rd_off(D0, 0, 0)>(vb), h0 = tr_read<v_rd_off(D0, 0, 1)>(vb), l1 = tr_read<v_rd_off(D0, 1, 0)>(vb), h1 = tr_read<v_rd_off(D0, 1, 1)>(vb);
;   const s16x4 l2 = tr_read<v_rd_off(D0, 2, 0)>(vb), h2 = tr_read<v_rd_off(D0, 2, 1)>(vb), l3 = tr_read<v_rd_off(D0, 3, 0)>(vb), h3 = tr_read<v_rd_off(D0, 3, 1)>(vb);
;   asm volatile("s_waitcnt lgkmcnt(0)" ::: "memory"); SBAR();
;     ...
;   od = __builtin_amdgcn_mfma_f32_32x32x16_bf16(pa0, PK(l0, h0), od, 0, 0, 0);
;   od = __builtin_amdgcn_mfma_f32_32x32x16_bf16(pa1, PK(l1, h1), od, 0, 0, 0);
;   od = __builtin_amdgcn_mfma_f32_32x32x16_bf16(pa2, PK(l2, h2), od, 0, 0, 0);
;   od = __builtin_amdgcn_mfma_f32_32x32x16_bf16(pa3, PK(l3, h3), od, 0, 0, 0);
;     ...
; }
; DI void pv_d0(f32x16* o, int vb, bf16x8 pa0, bf16x8 pa1, bf16x8 pa2, bf16x8 pa3) {
;   pv_one<0>(o[0], vb, pa0, pa1, pa2, pa3); pv_one<1>(o[1], vb, pa0, pa1, pa2, pa3); pv_one<2>(o[2], vb, pa0, pa1, pa2, pa3); pv_one<3>(o[3], vb, pa0, pa1, pa2, pa3);
; }
	s_nop 0
	v_mfma_f32_32x32x16_bf16 v[0:15], v[160:163], v[232:235], v[0:15]
	ds_read_b64_tr_b16 v[232:233], v202 offset:0x200
	ds_read_b64_tr_b16 v[234:235], v202 offset:0xa00
	s_waitcnt lgkmcnt(6)
	v_mfma_f32_32x32x16_bf16 v[0:15], v[164:167], v[236:239], v[0:15]
	ds_read_b64_tr_b16 v[236:237], v202 offset:0x1200
	ds_read_b64_tr_b16 v[238:239], v202 offset:0x1a00
	s_waitcnt lgkmcnt(6)
	v_mfma_f32_32x32x16_bf16 v[0:15], v[170:173], v[240:243], v[0:15]
	ds_read_b64_tr_b16 v[240:241], v202 offset:0x2200
	ds_read_b64_tr_b16 v[242:243], v202 offset:0x2a00
	s_waitcnt lgkmcnt(6)
	v_mfma_f32_32x32x16_bf16 v[0:15], v[218:221], v[244:247], v[0:15]
	ds_read_b64_tr_b16 v[244:245], v202 offset:0x3200
	ds_read_b64_tr_b16 v[246:247], v202 offset:0x3a00
	s_waitcnt lgkmcnt(6)
	v_mfma_f32_32x32x16_bf16 v[48:63], v[160:163], v[232:235], v[48:63]
	ds_read_b64_tr_b16 v[232:233], v202 offset:0x400
	ds_read_b64_tr_b16 v[234:235], v202 offset:0xc00
	s_waitcnt lgkmcnt(6)
	v_mfma_f32_32x32x16_bf16 v[48:63], v[164:167], v[236:239], v[48:63]
	ds_read_b64_tr_b16 v[236:237], v202 offset:0x1400
	ds_read_b64_tr_b16 v[238:239], v202 offset:0x1c00
	s_waitcnt lgkmcnt(6)
	v_mfma_f32_32x32x16_bf16 v[48:63], v[170:173], v[240:243], v[48:63]
	ds_read_b64_tr_b16 v[240:241], v202 offset:0x2400
	ds_read_b64_tr_b16 v[242:243], v202 offset:0x2c00
	s_waitcnt lgkmcnt(6)
	v_mfma_f32_32x32x16_bf16 v[48:63], v[218:221], v[244:247], v[48:63]
	ds_read_b64_tr_b16 v[244:245], v202 offset:0x3400
	ds_read_b64_tr_b16 v[246:247], v202 offset:0x3c00
	s_waitcnt lgkmcnt(6)
	v_mfma_f32_32x32x16_bf16 v[32:47], v[160:163], v[232:235], v[32:47]
	ds_read_b64_tr_b16 v[232:233], v202 offset:0x600
	ds_read_b64_tr_b16 v[234:235], v202 offset:0xe00
	s_waitcnt lgkmcnt(6)
	v_mfma_f32_32x32x16_bf16 v[32:47], v[164:167], v[236:239], v[32:47]
	ds_read_b64_tr_b16 v[236:237], v202 offset:0x1600
	ds_read_b64_tr_b16 v[238:239], v202 offset:0x1e00
	s_waitcnt lgkmcnt(6)
	v_mfma_f32_32x32x16_bf16 v[32:47], v[170:173], v[240:243], v[32:47]
	ds_read_b64_tr_b16 v[240:241], v202 offset:0x2600
	ds_read_b64_tr_b16 v[242:243], v202 offset:0x2e00
	s_waitcnt lgkmcnt(6)
	v_mfma_f32_32x32x16_bf16 v[32:47], v[218:221], v[244:247], v[32:47]
	ds_read_b64_tr_b16 v[244:245], v202 offset:0x3600
	ds_read_b64_tr_b16 v[246:247], v202 offset:0x3e00
	s_waitcnt lgkmcnt(6)
	v_mfma_f32_32x32x16_bf16 v[16:31], v[160:163], v[232:235], v[16:31]
	v_max_f32_e32 v160, v81, v81
	v_max_f32_e32 v161, v80, v80
	v_max_f32_e32 v160, v161, v160
	v_max3_f32 v160, v160, v82, v83
	v_max3_f32 v160, v160, v84, v85
	v_max3_f32 v160, v160, v86, v87
	v_max3_f32 v160, v160, v88, v89
	v_max3_f32 v160, v160, v90, v91
	v_max3_f32 v160, v160, v92, v93
	s_waitcnt lgkmcnt(4)
	v_mfma_f32_32x32x16_bf16 v[16:31], v[164:167], v[236:239], v[16:31]
	v_max3_f32 v160, v160, v94, v95
	v_max3_f32 v160, v160, v64, v65
	v_max3_f32 v160, v160, v66, v67
	v_max3_f32 v160, v160, v68, v69
	v_max3_f32 v160, v160, v70, v71
	v_max3_f32 v160, v160, v72, v73
	v_max3_f32 v160, v160, v74, v75
	v_max3_f32 v160, v160, v76, v77
	s_waitcnt lgkmcnt(2)
	v_mfma_f32_32x32x16_bf16 v[16:31], v[170:173], v[240:243], v[16:31]
	v_max3_f32 v160, v160, v78, v79
	v_mov_b32_e32 v161, v160
	s_nop 1
	v_permlane32_swap_b32_e32 v160, v161
	v_max_f32_e32 v161, v161, v161
	v_max_f32_e32 v160, v160, v160
	v_max_f32_e32 v160, v160, v161
	v_sub_f32_e32 v161, v160, v168
	v_cmp_ge_f32_e32 vcc, s95, v161
	v_max_f32_e32 v161, v168, v168
	v_max_f32_e32 v160, v161, v160
	s_waitcnt lgkmcnt(0)
	v_mfma_f32_32x32x16_bf16 v[16:31], v[218:221], v[244:247], v[16:31]
	v_sub_f32_e32 v161, v168, v160
	v_mul_f32_e32 v161, 0x3e0293ee, v161
	v_exp_f32_e32 v161, v161
	s_cmp_eq_u64 vcc, exec
	s_cselect_b64 s[0:1], -1, 0
	s_barrier
	s_waitcnt vmcnt(4)
	v_cndmask_b32_e64 v218, v161, 1.0, s[0:1]
	v_cmp_gt_f32_e32 vcc, 1.0, v218
	s_waitcnt vmcnt(7)
	ds_write_b128 v204, v[128:131]
	s_waitcnt vmcnt(6)
	ds_write_b128 v205, v[136:139]
	s_cbranch_vccz .LBB0_839
	s_and_saveexec_b64 s[10:11], s[4:5]
	ds_write_b32 v199, v218 offset:128
	s_or_b64 exec, exec, s[10:11]
	s_waitcnt lgkmcnt(0)
	v_add_u32_e32 v161, v198, v180
	ds_read_b128 v[162:165], v161 offset:224
	ds_read_b128 v[170:173], v161 offset:192
	ds_read_b128 v[220:223], v161 offset:160
	ds_read_b128 v[232:235], v161 offset:128
	s_waitcnt lgkmcnt(3)
	v_pk_mul_f32 v[12:13], v[12:13], v[162:163]
	s_waitcnt lgkmcnt(2)
	v_pk_mul_f32 v[8:9], v[8:9], v[170:171]
	s_waitcnt lgkmcnt(1)
	v_pk_mul_f32 v[4:5], v[4:5], v[220:221]
	v_pk_mul_f32 v[14:15], v[14:15], v[164:165]
	v_pk_mul_f32 v[10:11], v[10:11], v[172:173]
	v_pk_mul_f32 v[6:7], v[6:7], v[222:223]
	s_waitcnt lgkmcnt(0)
	v_pk_mul_f32 v[2:3], v[2:3], v[234:235]
	v_pk_mul_f32 v[0:1], v[0:1], v[232:233]
	v_pk_mul_f32 v[60:61], v[60:61], v[162:163]
	v_pk_mul_f32 v[56:57], v[56:57], v[170:171]
	v_pk_mul_f32 v[52:53], v[52:53], v[220:221]
	v_pk_mul_f32 v[62:63], v[62:63], v[164:165]
	v_pk_mul_f32 v[58:59], v[58:59], v[172:173]
	v_pk_mul_f32 v[54:55], v[54:55], v[222:223]
	v_pk_mul_f32 v[50:51], v[50:51], v[234:235]
	v_pk_mul_f32 v[48:49], v[48:49], v[232:233]
	v_pk_mul_f32 v[44:45], v[44:45], v[162:163]
	v_pk_mul_f32 v[40:41], v[40:41], v[170:171]
	v_pk_mul_f32 v[36:37], v[36:37], v[220:221]
	v_pk_mul_f32 v[46:47], v[46:47], v[164:165]
	v_pk_mul_f32 v[42:43], v[42:43], v[172:173]
	v_pk_mul_f32 v[38:39], v[38:39], v[222:223]
	v_pk_mul_f32 v[34:35], v[34:35], v[234:235]
	v_pk_mul_f32 v[32:33], v[32:33], v[232:233]
	v_pk_mul_f32 v[28:29], v[28:29], v[162:163]
	v_pk_mul_f32 v[24:25], v[24:25], v[170:171]
	v_pk_mul_f32 v[20:21], v[20:21], v[220:221]
	v_pk_mul_f32 v[30:31], v[30:31], v[164:165]
	v_pk_mul_f32 v[26:27], v[26:27], v[172:173]
	v_pk_mul_f32 v[22:23], v[22:23], v[222:223]
	v_pk_mul_f32 v[18:19], v[18:19], v[234:235]
	v_pk_mul_f32 v[16:17], v[16:17], v[232:233]
; DI void partialSM(f32x16& p0, f32x16& p1, float& m_reg, float& mn, float& alpha) {
;   constexpr float C = SCALE * 1.4426950408889634f;
;   float pmax = p0[0]; for (int r = 1; r < 16; ++r) pmax = fmaxf(pmax, p0[r]); for (int r = 0; r < 16; ++r) pmax = fmaxf(pmax, p1[r]);
;   { auto rr = __builtin_amdgcn_permlane32_swap(__float_as_uint(pmax), __float_as_uint(pmax), false, false);
;     pmax = fmaxf(__uint_as_float(rr[0]), __uint_as_float(rr[1])); }
;   if (__builtin_expect(__all(pmax - m_reg <= THR / SCALE), 1)) { mn = m_reg; alpha = 1.f; }
;   else { mn = fmaxf(m_reg, pmax); alpha = __builtin_amdgcn_exp2f((m_reg - mn) * C); m_reg = mn; }
;   float mnC = -mn * C;
;   for (int r = 0; r < 16; ++r) p0[r] = fmaf(p0[r], C, mnC); for (int r = 0; r < 16; ++r) p1[r] = fmaf(p1[r], C, mnC);
;   for (int r = 0; r < 16; ++r) p0[r] = __builtin_amdgcn_exp2f(p0[r]);
; }
; DI void finishSM(f32x16& p0, f32x16& p1, float alpha, float& l_reg, bf16x8& pa0, bf16x8& pa1, bf16x8& pa2, bf16x8& pa3) {
;   for (int r = 0; r < 16; ++r) p1[r] = __builtin_amdgcn_exp2f(p1[r]);
;   float ps = 0; for (int r = 0; r < 16; ++r) ps += p0[r]; for (int r = 0; r < 16; ++r) ps += p1[r];
;   { auto rr = __builtin_amdgcn_permlane32_swap(__float_as_uint(ps), __float_as_uint(ps), false, false);
;     ps = __uint_as_float(rr[0]) + __uint_as_float(rr[1]); }
;   l_reg = l_reg * alpha + ps;
;     ...
;   PK4(p0, 0, pa0); PK4(p0, 8, pa1); PK4(p1, 0, pa2); PK4(p1, 8, pa3);
;     ...
; }
; DI void qkt(f32x16& p0, f32x16& p1, const bf16_t* Ks, const bf16x8* qr, int r32, int hi) {
;   p0 = f32x16{}; p1 = f32x16{};
;   for (int d0 = 0; d0 < 8; ++d0) { int cb = (d0 * 16 + hi * 8) * 2;
;     bf16x8 b0 = *reinterpret_cast<const bf16x8*>((const char*)Ks + KSWZ(r32, cb));
;     bf16x8 b1 = *reinterpret_cast<const bf16x8*>((const char*)Ks + KSWZ(32 + r32, cb));
;     p0 = __builtin_amdgcn_mfma_f32_32x32x16_bf16(b0, qr[d0], p0, 0, 0, 0);
;     p1 = __builtin_amdgcn_mfma_f32_32x32x16_bf16(b1, qr[d0], p1, 0, 0, 0); }
; }
.LBB0_839:
	v_cndmask_b32_e64 v219, v160, v168, s[0:1]
	v_mul_f32_e32 v220, 0xbe0293ee, v219
	v_fmamk_f32 v80, v80, 0x3e0293ee, v220
	v_fmamk_f32 v81, v81, 0x3e0293ee, v220
	v_fmamk_f32 v82, v82, 0x3e0293ee, v220
	v_fmamk_f32 v83, v83, 0x3e0293ee, v220
	v_fmamk_f32 v84, v84, 0x3e0293ee, v220
	v_fmamk_f32 v85, v85, 0x3e0293ee, v220
	v_fmamk_f32 v86, v86, 0x3e0293ee, v220
	v_fmamk_f32 v87, v87, 0x3e0293ee, v220
	v_fmamk_f32 v88, v88, 0x3e0293ee, v220
	v_fmamk_f32 v89, v89, 0x3e0293ee, v220
	v_fmamk_f32 v90, v90, 0x3e0293ee, v220
	v_fmamk_f32 v91, v91, 0x3e0293ee, v220
	v_fmamk_f32 v92, v92, 0x3e0293ee, v220
	v_fmamk_f32 v93, v93, 0x3e0293ee, v220
	v_fmamk_f32 v94, v94, 0x3e0293ee, v220
	v_fmamk_f32 v95, v95, 0x3e0293ee, v220
	v_exp_f32_e32 v160, v80
	v_exp_f32_e32 v175, v81
	v_exp_f32_e32 v161, v82
	v_exp_f32_e32 v174, v83
	v_exp_f32_e32 v162, v84
	v_exp_f32_e32 v173, v85
	v_exp_f32_e32 v163, v86
	v_exp_f32_e32 v172, v87
	v_exp_f32_e32 v164, v88
	v_exp_f32_e32 v171, v89
	v_exp_f32_e32 v165, v90
	v_exp_f32_e32 v170, v91
	v_exp_f32_e32 v166, v92
	v_exp_f32_e32 v169, v93
	v_exp_f32_e32 v167, v94
	v_exp_f32_e32 v168, v95
	v_fmamk_f32 v236, v64, 0x3e0293ee, v220
	v_fmamk_f32 v237, v65, 0x3e0293ee, v220
	v_fmamk_f32 v238, v66, 0x3e0293ee, v220
	v_fmamk_f32 v239, v67, 0x3e0293ee, v220
	v_fmamk_f32 v240, v68, 0x3e0293ee, v220
	v_fmamk_f32 v222, v69, 0x3e0293ee, v220
	v_fmamk_f32 v223, v70, 0x3e0293ee, v220
	v_fmamk_f32 v231, v71, 0x3e0293ee, v220
	v_fmamk_f32 v232, v72, 0x3e0293ee, v220
	v_fmamk_f32 v233, v73, 0x3e0293ee, v220
	v_fmamk_f32 v234, v74, 0x3e0293ee, v220
	v_fmamk_f32 v235, v75, 0x3e0293ee, v220
	v_fmamk_f32 v221, v76, 0x3e0293ee, v220
	v_fmamk_f32 v241, v77, 0x3e0293ee, v220
	v_fmamk_f32 v242, v78, 0x3e0293ee, v220
	v_fmac_f32_e32 v220, 0x3e0293ee, v79
	s_waitcnt lgkmcnt(0)
	ds_read_b128 v[64:67], v207 offset:32768
	ds_read_b128 v[68:71], v207 offset:40960
	ds_read_b128 v[244:247], v210 offset:32768
	ds_read_b128 v[248:251], v210 offset:40960
	v_exp_f32_e32 v226, v238
	v_exp_f32_e32 v238, v220
	s_waitcnt lgkmcnt(3)
	v_mfma_f32_32x32x16_bf16 v[80:95], v[64:67], v[116:119], 0
	v_add_f32_e32 v220, 0, v160
	v_add_f32_e32 v220, v175, v220
	v_add_f32_e32 v220, v161, v220
	v_add_f32_e32 v220, v174, v220
	v_add_f32_e32 v220, v162, v220
	v_add_f32_e32 v220, v173, v220
	v_add_f32_e32 v220, v163, v220
	s_waitcnt lgkmcnt(2)
	v_mfma_f32_32x32x16_bf16 v[64:79], v[68:71], v[116:119], 0
	ds_read_b128 v[128:131], v211 offset:32768
	ds_read_b128 v[132:135], v211 offset:40960
	v_add_f32_e32 v220, v172, v220
	v_add_f32_e32 v220, v164, v220
	v_add_f32_e32 v220, v171, v220
	v_add_f32_e32 v220, v165, v220
	v_add_f32_e32 v220, v170, v220
	v_exp_f32_e32 v224, v236
	v_add_f32_e32 v220, v166, v220
	s_waitcnt lgkmcnt(3)
	v_mfma_f32_32x32x16_bf16 v[80:95], v[244:247], v[124:127], v[80:95]
	v_exp_f32_e32 v225, v237
	v_add_f32_e32 v220, v169, v220
	v_add_f32_e32 v220, v167, v220
	v_exp_f32_e32 v227, v239
	v_add_f32_e32 v220, v168, v220
	v_exp_f32_e32 v228, v240
	v_add_f32_e32 v220, v224, v220
	s_waitcnt lgkmcnt(2)
	v_mfma_f32_32x32x16_bf16 v[64:79], v[248:251], v[124:127], v[64:79]
	ds_read_b128 v[244:247], v208 offset:32768
	ds_read_b128 v[248:251], v208 offset:40960
	v_exp_f32_e32 v222, v222
	v_add_f32_e32 v220, v225, v220
	v_exp_f32_e32 v223, v223
	v_add_f32_e32 v220, v226, v220
	v_exp_f32_e32 v229, v231
	v_add_f32_e32 v220, v227, v220
	s_waitcnt lgkmcnt(3)
	v_mfma_f32_32x32x16_bf16 v[80:95], v[128:131], v[120:123], v[80:95]
	v_exp_f32_e32 v231, v232
	v_add_f32_e32 v220, v228, v220
	v_exp_f32_e32 v232, v233
	v_add_f32_e32 v220, v222, v220
	v_exp_f32_e32 v233, v234
	v_add_f32_e32 v220, v223, v220
	v_exp_f32_e32 v234, v235
	s_waitcnt lgkmcnt(2)
	v_mfma_f32_32x32x16_bf16 v[64:79], v[132:135], v[120:123], v[64:79]
	ds_read_b128 v[128:131], v209 offset:32768
	ds_read_b128 v[132:135], v209 offset:40960
	v_add_f32_e32 v220, v229, v220
	v_exp_f32_e32 v235, v221
	v_add_f32_e32 v220, v231, v220
	v_exp_f32_e32 v236, v241
	v_add_f32_e32 v220, v232, v220
	v_exp_f32_e32 v237, v242
	s_waitcnt lgkmcnt(3)
	v_mfma_f32_32x32x16_bf16 v[80:95], v[244:247], v[112:115], v[80:95]
	v_add_f32_e32 v220, v233, v220
	v_add_f32_e32 v220, v234, v220
	v_add_f32_e32 v220, v235, v220
	v_add_f32_e32 v220, v236, v220
	v_add_f32_e32 v220, v237, v220
	v_add_f32_e32 v220, v238, v220
	v_mov_b32_e32 v221, v220
	s_waitcnt lgkmcnt(2)
	v_mfma_f32_32x32x16_bf16 v[64:79], v[248:251], v[112:115], v[64:79]
	ds_read_b128 v[244:247], v212 offset:32768
	ds_read_b128 v[248:251], v212 offset:40960
	v_permlane32_swap_b32_e32 v220, v221
	s_waitcnt lgkmcnt(3)
	v_mfma_f32_32x32x16_bf16 v[80:95], v[128:131], v[108:111], v[80:95]
	s_waitcnt lgkmcnt(2)
	v_mfma_f32_32x32x16_bf16 v[64:79], v[132:135], v[108:111], v[64:79]
	ds_read_b128 v[128:131], v213 offset:32768
	ds_read_b128 v[132:135], v213 offset:40960
	s_waitcnt lgkmcnt(3)
	v_mfma_f32_32x32x16_bf16 v[80:95], v[244:247], v[104:107], v[80:95]
	s_waitcnt lgkmcnt(2)
	v_mfma_f32_32x32x16_bf16 v[64:79], v[248:251], v[104:107], v[64:79]
	ds_read_b128 v[244:247], v214 offset:32768
	ds_read_b128 v[248:251], v214 offset:40960
	s_waitcnt lgkmcnt(3)
	v_mfma_f32_32x32x16_bf16 v[80:95], v[128:131], v[100:103], v[80:95]
	s_waitcnt lgkmcnt(2)
	v_mfma_f32_32x32x16_bf16 v[64:79], v[132:135], v[100:103], v[64:79]
	v_cvt_pk_bf16_f32 v160, v160, v175
	v_cvt_pk_bf16_f32 v161, v161, v174
	v_cvt_pk_bf16_f32 v162, v162, v173
	v_cvt_pk_bf16_f32 v163, v163, v172
	v_cvt_pk_bf16_f32 v164, v164, v171
	v_cvt_pk_bf16_f32 v165, v165, v170
	s_waitcnt lgkmcnt(1)
	v_mfma_f32_32x32x16_bf16 v[80:95], v[244:247], v[96:99], v[80:95]
	v_cvt_pk_bf16_f32 v166, v166, v169
	v_cvt_pk_bf16_f32 v167, v167, v168
	v_cvt_pk_bf16_f32 v168, v224, v225
	v_cvt_pk_bf16_f32 v169, v226, v227
	v_cvt_pk_bf16_f32 v170, v228, v222
	v_cvt_pk_bf16_f32 v171, v223, v229
	v_cvt_pk_bf16_f32 v172, v231, v232
	s_waitcnt lgkmcnt(0)
	v_mfma_f32_32x32x16_bf16 v[64:79], v[248:251], v[96:99], v[64:79]
	v_cvt_pk_bf16_f32 v173, v233, v234
	v_cvt_pk_bf16_f32 v174, v235, v236
	v_cvt_pk_bf16_f32 v175, v237, v238
	v_permlane32_swap_b32_e32 v160, v162
	v_permlane32_swap_b32_e32 v161, v163
	v_permlane32_swap_b32_e32 v164, v166
	v_permlane32_swap_b32_e32 v165, v167
	v_permlane32_swap_b32_e32 v168, v170
	v_permlane32_swap_b32_e32 v169, v171
	v_permlane32_swap_b32_e32 v172, v174
	v_permlane32_swap_b32_e32 v173, v175
	s_waitcnt vmcnt(0)
	ds_write_b128 v203, v[152:155] offset:49152
	ds_write_b128 v206, v[156:159] offset:49152
	s_cmp_ge_u32 s16, s15
	s_cselect_b64 s[10:11], -1, 0
	s_and_b64 vcc, exec, s[10:11]
	s_cbranch_vccnz .LBB0_841
	v_add_co_u32_e32 v128, vcc, 0xffffc000, v194
	s_nop 1
	v_addc_co_u32_e32 v129, vcc, -1, v195, vcc
	v_add_co_u32_e32 v132, vcc, 0xfeefc000, v194
	s_nop 1
	v_addc_co_u32_e32 v133, vcc, -1, v195, vcc
	v_add_co_u32_e32 v140, vcc, 0xfef00000, v194
	global_load_dwordx4 v[128:131], v[128:129], off
	s_nop 0
	global_load_dwordx4 v[132:135], v[132:133], off
	v_addc_co_u32_e32 v141, vcc, -1, v195, vcc
	global_load_dwordx4 v[136:139], v[194:195], off
	s_nop 0
	global_load_dwordx4 v[140:143], v[140:141], off
